# first K-iteration peeled with C=0 MFMAs (no accumulator zeroing) in up/proj GEMMs, on top of v60
# speedup vs baseline: 1.0036x; 1.0036x over previous
; #define PG8_STAGE(bufoff, gbase, voff) do { _Pragma("unroll") for (int _i = 0; _i < 2; ++_i) \
;         __builtin_amdgcn_global_load_lds((const unsigned*)((const char*)(gbase) + (voff)[_i]), (PG8_LAS unsigned*)(lds + (bufoff) + ldsw + _i * 8192), 16, 0, 0); } while (0)
; #define PG8_LDA(dst, b, h) do { _Pragma("unroll") for (int m = 0; m < 4; ++m) _Pragma("unroll") for (int k = 0; k < 2; ++k) dst[m][k] = *(const PG8_LAS bf16x8*)(lds + PG8_SA(b, h) + aoff + m * 2048 + k * 1024); } while (0)
; #define PG8_LDB(dst, b, h) do { _Pragma("unroll") for (int n = 0; n < 2; ++n) _Pragma("unroll") for (int k = 0; k < 2; ++k) dst[n][k] = *(const PG8_LAS bf16x8*)(lds + PG8_SB(b, h) + boff + n * 2048 + k * 1024); } while (0)
; #define PG8_WAIT_V(n) asm volatile("s_waitcnt vmcnt(" #n ")" ::: "memory")
; #define PG8_WAIT_L(n) asm volatile("s_waitcnt lgkmcnt(" #n ")" ::: "memory")
; #define PG8_BAR __builtin_amdgcn_s_barrier()
; template <class Epi, class Sched, bool ALIGN_EPI = false, bool SP2 = false>
; __device__ __forceinline__ void gemm_phase(PG8_LAS unsigned char* lds, const Gemm g, const Sched& S, const Epi& E, const int tid) {
;     ...
;         const bool has_next = S.next(ui + 1, nxt);
;         const char* nA = has_next ? (const char*)g.A + (size_t)nxt.pm * tstep : cA; const char* nB = has_next ? (const char*)g.Bt + (size_t)nxt.pn * tstep : cB;
;         for (int t = 0; t < nt; t += 2) {
;             if constexpr (Epi::MIDK) { if (t == E.midk) E.mid(acc, cur, wr, fr); }
;             const bool last = (t == nt - 2);
;             const char* a1 = cA + (size_t)(t + 1) * kstep;
;             const char* a2 = last ? nA : cA + (size_t)(t + 2) * kstep; const char* b2 = last ? nB : cB + (size_t)(t + 2) * kstep;
;             const char* a3 = a2 + kstep; const char* b3 = b2 + kstep;
;             if (last && has_next) S.a_ready(nxt);
;             if constexpr (SP2) {
;             PG8_LDB(B0, 0, 0); PG8_LDB(B1, 0, 1); PG8_SCHED; PG8_LDA(At, 0, 0); PG8_STAGE(PG8_SA(1, 1), a1 + hstep, voffA);
;             PG8_WAIT_V(8); PG8_WAIT_L(0); PG8_BAR; PG8_MMA(0, 0, At, B0); PG8_MMA(0, 1, At, B1); PG8_BAR; PG8_SCHED;
;             PG8_LDA(At, 0, 1); PG8_STAGE(PG8_SB(0, 0), b2, voffB); PG8_STAGE(PG8_SB(0, 1), b2 + hstep, voffB); PG8_STAGE(PG8_SA(0, 0), a2, voffA);
;             PG8_WAIT_V(8); PG8_WAIT_L(0); PG8_BAR; PG8_MMA(1, 0, At, B0); PG8_MMA(1, 1, At, B1); PG8_BAR; PG8_SCHED;
.LBB0_187:
	s_ashr_i32 s75, s74, 31
	s_lshl_b64 s[36:37], s[74:75], 19
	s_add_u32 s78, s13, s36
	s_addc_u32 s79, s14, s37
	s_and_b64 s[36:37], s[4:5], exec
	s_cselect_b32 s34, s79, s83
	s_cselect_b32 s36, s78, s82
	s_ashr_i32 s77, s76, 31
	s_lshl_b64 s[42:43], s[76:77], 19
	s_add_u32 s80, s17, s42
	s_addc_u32 s81, s18, s43
	s_and_b64 s[42:43], s[4:5], exec
	s_cselect_b32 s37, s81, s85
	s_cselect_b32 s38, s80, s84
	s_add_u32 s40, s84, 0x100
	s_addc_u32 s42, s85, 0
	s_add_u32 s82, s82, 0x40080
	s_addc_u32 s83, s83, 0
	s_mov_b32 s43, -2
	s_waitcnt vmcnt(0)
	s_add_u32 s46, s82, 0xfffc0080
	s_addc_u32 s54, s83, -1
	s_add_i32 s55, 0, 0x10000
	s_cmp_eq_u32 s43, 12
	s_cselect_b32 s87, s34, s54
	s_cselect_b32 s86, s36, s46
	v_add_u32_e32 v149, s55, v146
	s_cselect_b32 s85, s37, s42
	s_cselect_b32 s84, s38, s40
	s_add_i32 s46, 0, 0x14000
	ds_read_b128 v[142:145], v149
	ds_read_b128 v[150:153], v149 offset:1024
	ds_read_b128 v[154:157], v149 offset:2048
	ds_read_b128 v[158:161], v149 offset:3072
	v_add_u32_e32 v149, s46, v146
	ds_read_b128 v[162:165], v149
	ds_read_b128 v[166:169], v149 offset:1024
	ds_read_b128 v[170:173], v149 offset:2048
	ds_read_b128 v[174:177], v149 offset:3072
	v_lshl_add_u64 v[194:195], s[82:83], 0, v[140:141]
	s_add_i32 m0, s20, 0xc000
	ds_read_b128 v[178:181], v148
	ds_read_b128 v[182:185], v148 offset:1024
	ds_read_b128 v[186:189], v148 offset:2048
	ds_read_b128 v[190:193], v148 offset:3072
	ds_read_b128 v[208:211], v148 offset:4096
	ds_read_b128 v[226:229], v148 offset:5120
	ds_read_b128 v[230:233], v148 offset:6144
	ds_read_b128 v[234:237], v148 offset:7168
	global_load_lds_dwordx4 v[194:195], off
	v_lshl_add_u64 v[194:195], s[82:83], 0, v[138:139]
	s_add_i32 m0, s20, 0xe000
	s_nop 0
	global_load_lds_dwordx4 v[194:195], off
	s_waitcnt vmcnt(8)
	s_waitcnt lgkmcnt(0)
	s_barrier
	s_setprio 1
	s_waitcnt lgkmcnt(0)
	v_mfma_f32_16x16x32_bf16 v[126:129], v[142:145], v[178:181], 0
	v_mfma_f32_16x16x32_bf16 v[118:121], v[154:157], v[178:181], 0
	v_mfma_f32_16x16x32_bf16 v[110:113], v[142:145], v[186:189], 0
	v_mfma_f32_16x16x32_bf16 v[102:105], v[154:157], v[186:189], 0
	v_mfma_f32_16x16x32_bf16 v[94:97], v[142:145], v[208:211], 0
	v_mfma_f32_16x16x32_bf16 v[86:89], v[154:157], v[208:211], 0
	v_mfma_f32_16x16x32_bf16 v[78:81], v[142:145], v[230:233], 0
	v_mfma_f32_16x16x32_bf16 v[70:73], v[154:157], v[230:233], 0
	v_mfma_f32_16x16x32_bf16 v[126:129], v[150:153], v[182:185], v[126:129]
	v_mfma_f32_16x16x32_bf16 v[118:121], v[158:161], v[182:185], v[118:121]
	v_mfma_f32_16x16x32_bf16 v[110:113], v[150:153], v[190:193], v[110:113]
	v_mfma_f32_16x16x32_bf16 v[102:105], v[158:161], v[190:193], v[102:105]
	v_mfma_f32_16x16x32_bf16 v[94:97], v[150:153], v[226:229], v[94:97]
	v_mfma_f32_16x16x32_bf16 v[86:89], v[158:161], v[226:229], v[86:89]
	v_mfma_f32_16x16x32_bf16 v[78:81], v[150:153], v[234:237], v[78:81]
	v_mfma_f32_16x16x32_bf16 v[70:73], v[158:161], v[234:237], v[70:73]
	s_setprio 0
	s_setprio 1
	v_mfma_f32_16x16x32_bf16 v[130:133], v[162:165], v[178:181], 0
	v_mfma_f32_16x16x32_bf16 v[122:125], v[170:173], v[178:181], 0
	v_mfma_f32_16x16x32_bf16 v[114:117], v[162:165], v[186:189], 0
	v_mfma_f32_16x16x32_bf16 v[106:109], v[170:173], v[186:189], 0
	v_mfma_f32_16x16x32_bf16 v[98:101], v[162:165], v[208:211], 0
	v_mfma_f32_16x16x32_bf16 v[90:93], v[170:173], v[208:211], 0
	v_mfma_f32_16x16x32_bf16 v[82:85], v[162:165], v[230:233], 0
	v_mfma_f32_16x16x32_bf16 v[74:77], v[170:173], v[230:233], 0
	v_mfma_f32_16x16x32_bf16 v[130:133], v[166:169], v[182:185], v[130:133]
	v_mfma_f32_16x16x32_bf16 v[122:125], v[174:177], v[182:185], v[122:125]
	v_mfma_f32_16x16x32_bf16 v[114:117], v[166:169], v[190:193], v[114:117]
	v_mfma_f32_16x16x32_bf16 v[106:109], v[174:177], v[190:193], v[106:109]
	v_mfma_f32_16x16x32_bf16 v[98:101], v[166:169], v[226:229], v[98:101]
	v_mfma_f32_16x16x32_bf16 v[90:93], v[174:177], v[226:229], v[90:93]
	v_mfma_f32_16x16x32_bf16 v[82:85], v[166:169], v[234:237], v[82:85]
	v_mfma_f32_16x16x32_bf16 v[74:77], v[174:177], v[234:237], v[74:77]
	s_setprio 0
	s_barrier
	s_add_i32 s54, s55, s19
	v_lshl_add_u64 v[194:195], s[84:85], 0, v[0:1]
	s_mov_b32 m0, s54
	ds_read_b128 v[178:181], v148 offset:16384
	ds_read_b128 v[182:185], v148 offset:17408
	ds_read_b128 v[186:189], v148 offset:18432
	ds_read_b128 v[190:193], v148 offset:19456
	ds_read_b128 v[208:211], v148 offset:20480
	ds_read_b128 v[226:229], v148 offset:21504
	ds_read_b128 v[230:233], v148 offset:22528
	ds_read_b128 v[234:237], v148 offset:23552
	global_load_lds_dwordx4 v[194:195], off
	s_add_i32 m0, s54, 0x2000
	s_add_u32 s54, s84, 0x40000
	v_lshl_add_u64 v[238:239], s[84:85], 0, v[2:3]
	s_addc_u32 s55, s85, 0
	s_add_i32 s46, s46, s19
	global_load_lds_dwordx4 v[238:239], off
	v_lshl_add_u64 v[240:241], s[54:55], 0, v[0:1]
	s_mov_b32 m0, s46
	v_lshl_add_u64 v[242:243], s[86:87], 0, v[134:135]
	global_load_lds_dwordx4 v[240:241], off
	v_lshl_add_u64 v[240:241], s[54:55], 0, v[2:3]
	s_add_i32 m0, s46, 0x2000
	s_nop 0
	global_load_lds_dwordx4 v[240:241], off
	v_lshl_add_u64 v[240:241], s[86:87], 0, v[136:137]
	s_mov_b32 m0, s20
	s_nop 0
	global_load_lds_dwordx4 v[240:241], off
	s_mov_b32 m0, s21
	s_nop 0
	global_load_lds_dwordx4 v[242:243], off
	s_waitcnt vmcnt(8)
	s_waitcnt lgkmcnt(0)
	s_barrier
; #define PG8_STAGE(bufoff, gbase, voff) do { _Pragma("unroll") for (int _i = 0; _i < 2; ++_i) \
;         __builtin_amdgcn_global_load_lds((const unsigned*)((const char*)(gbase) + (voff)[_i]), (PG8_LAS unsigned*)(lds + (bufoff) + ldsw + _i * 8192), 16, 0, 0); } while (0)
; #define PG8_LDA(dst, b, h) do { _Pragma("unroll") for (int m = 0; m < 4; ++m) _Pragma("unroll") for (int k = 0; k < 2; ++k) dst[m][k] = *(const PG8_LAS bf16x8*)(lds + PG8_SA(b, h) + aoff + m * 2048 + k * 1024); } while (0)
; #define PG8_LDB(dst, b, h) do { _Pragma("unroll") for (int n = 0; n < 2; ++n) _Pragma("unroll") for (int k = 0; k < 2; ++k) dst[n][k] = *(const PG8_LAS bf16x8*)(lds + PG8_SB(b, h) + boff + n * 2048 + k * 1024); } while (0)
; #define PG8_MMA(ai, bj, At, Bt) do { __builtin_amdgcn_s_setprio(1); _Pragma("unroll") for (int m = 0; m < 4; ++m) _Pragma("unroll") for (int n = 0; n < 2; ++n) _Pragma("unroll") for (int k = 0; k < 2; ++k) \
;         acc[ai][bj][m][n] = __builtin_amdgcn_mfma_f32_16x16x32_bf16(Bt[n][k], At[m][k], acc[ai][bj][m][n], 0, 0, 0); __builtin_amdgcn_s_setprio(0); } while (0)
; #define PG8_WAIT_V(n) asm volatile("s_waitcnt vmcnt(" #n ")" ::: "memory")
; #define PG8_WAIT_L(n) asm volatile("s_waitcnt lgkmcnt(" #n ")" ::: "memory")
; #define PG8_BAR __builtin_amdgcn_s_barrier()
; #define PG8_SCHED __builtin_amdgcn_sched_barrier(0)
; template <class Epi, class Sched, bool ALIGN_EPI = false, bool SP2 = false>
; __device__ __forceinline__ void gemm_phase(PG8_LAS unsigned char* lds, const Gemm g, const Sched& S, const Epi& E, const int tid) {
;     ...
;             PG8_WAIT_V(8); PG8_WAIT_L(0); PG8_BAR; PG8_MMA(1, 0, At, B0); PG8_MMA(1, 1, At, B1); PG8_BAR; PG8_SCHED;
;             PG8_LDB(B0, 1, 0); PG8_LDB(B1, 1, 1); PG8_SCHED; PG8_LDA(At, 1, 0); PG8_STAGE(PG8_SA(0, 1), a2 + hstep, voffA);
;             PG8_WAIT_V(8); PG8_WAIT_L(0); PG8_BAR; PG8_MMA(0, 0, At, B0); PG8_MMA(0, 1, At, B1); PG8_BAR; PG8_SCHED;
	s_setprio 1
	s_waitcnt lgkmcnt(0)
	v_mfma_f32_16x16x32_bf16 v[62:65], v[142:145], v[178:181], 0
	v_mfma_f32_16x16x32_bf16 v[54:57], v[154:157], v[178:181], 0
	v_mfma_f32_16x16x32_bf16 v[46:49], v[142:145], v[186:189], 0
	v_mfma_f32_16x16x32_bf16 v[38:41], v[154:157], v[186:189], 0
	v_mfma_f32_16x16x32_bf16 v[30:33], v[142:145], v[208:211], 0
	v_mfma_f32_16x16x32_bf16 v[22:25], v[154:157], v[208:211], 0
	v_mfma_f32_16x16x32_bf16 v[14:17], v[142:145], v[230:233], 0
	v_mfma_f32_16x16x32_bf16 v[10:13], v[154:157], v[230:233], 0
	v_mfma_f32_16x16x32_bf16 v[62:65], v[150:153], v[182:185], v[62:65]
	v_mfma_f32_16x16x32_bf16 v[54:57], v[158:161], v[182:185], v[54:57]
	v_mfma_f32_16x16x32_bf16 v[46:49], v[150:153], v[190:193], v[46:49]
	v_mfma_f32_16x16x32_bf16 v[38:41], v[158:161], v[190:193], v[38:41]
	v_mfma_f32_16x16x32_bf16 v[30:33], v[150:153], v[226:229], v[30:33]
	v_mfma_f32_16x16x32_bf16 v[22:25], v[158:161], v[226:229], v[22:25]
	v_mfma_f32_16x16x32_bf16 v[14:17], v[150:153], v[234:237], v[14:17]
	v_mfma_f32_16x16x32_bf16 v[10:13], v[158:161], v[234:237], v[10:13]
	s_setprio 0
	s_setprio 1
	v_mfma_f32_16x16x32_bf16 v[66:69], v[162:165], v[178:181], 0
	v_mfma_f32_16x16x32_bf16 v[58:61], v[170:173], v[178:181], 0
	v_mfma_f32_16x16x32_bf16 v[50:53], v[162:165], v[186:189], 0
	v_mfma_f32_16x16x32_bf16 v[42:45], v[170:173], v[186:189], 0
	v_mfma_f32_16x16x32_bf16 v[34:37], v[162:165], v[208:211], 0
	v_mfma_f32_16x16x32_bf16 v[26:29], v[170:173], v[208:211], 0
	v_mfma_f32_16x16x32_bf16 v[18:21], v[162:165], v[230:233], 0
	v_mfma_f32_16x16x32_bf16 v[6:9], v[170:173], v[230:233], 0
	v_mfma_f32_16x16x32_bf16 v[66:69], v[166:169], v[182:185], v[66:69]
	v_mfma_f32_16x16x32_bf16 v[58:61], v[174:177], v[182:185], v[58:61]
	v_mfma_f32_16x16x32_bf16 v[50:53], v[166:169], v[190:193], v[50:53]
	v_mfma_f32_16x16x32_bf16 v[42:45], v[174:177], v[190:193], v[42:45]
	v_mfma_f32_16x16x32_bf16 v[34:37], v[166:169], v[226:229], v[34:37]
	v_mfma_f32_16x16x32_bf16 v[26:29], v[174:177], v[226:229], v[26:29]
	v_mfma_f32_16x16x32_bf16 v[18:21], v[166:169], v[234:237], v[18:21]
	v_mfma_f32_16x16x32_bf16 v[6:9], v[174:177], v[234:237], v[6:9]
	s_setprio 0
	s_barrier
	s_add_i32 s46, 0, 0x18000
	v_add_u32_e32 v149, s46, v146
	s_add_i32 s75, 0, 0x1c000
	ds_read_b128 v[142:145], v149
	ds_read_b128 v[150:153], v149 offset:1024
	ds_read_b128 v[154:157], v149 offset:2048
	ds_read_b128 v[158:161], v149 offset:3072
	v_add_u32_e32 v149, s75, v146
	ds_read_b128 v[162:165], v149
	ds_read_b128 v[166:169], v149 offset:1024
	ds_read_b128 v[170:173], v149 offset:2048
	ds_read_b128 v[174:177], v149 offset:3072
	s_add_u32 s54, s86, 0x40000
	s_addc_u32 s55, s87, 0
	s_mov_b32 m0, s24
	v_lshl_add_u64 v[244:245], s[54:55], 0, v[136:137]
	ds_read_b128 v[178:181], v148 offset:32768
	ds_read_b128 v[182:185], v148 offset:33792
	ds_read_b128 v[186:189], v148 offset:34816
	ds_read_b128 v[190:193], v148 offset:35840
	ds_read_b128 v[208:211], v148 offset:36864
	ds_read_b128 v[226:229], v148 offset:37888
	ds_read_b128 v[230:233], v148 offset:38912
	ds_read_b128 v[234:237], v148 offset:39936
	global_load_lds_dwordx4 v[244:245], off
	v_lshl_add_u64 v[244:245], s[54:55], 0, v[134:135]
	s_mov_b32 m0, s25
	s_nop 0
	global_load_lds_dwordx4 v[244:245], off
	s_waitcnt vmcnt(8)
	s_waitcnt lgkmcnt(0)
	s_barrier
	s_setprio 1
	s_waitcnt lgkmcnt(0)
	v_mfma_f32_16x16x32_bf16 v[126:129], v[142:145], v[178:181], v[126:129]
	v_mfma_f32_16x16x32_bf16 v[118:121], v[154:157], v[178:181], v[118:121]
	v_mfma_f32_16x16x32_bf16 v[110:113], v[142:145], v[186:189], v[110:113]
	v_mfma_f32_16x16x32_bf16 v[102:105], v[154:157], v[186:189], v[102:105]
	v_mfma_f32_16x16x32_bf16 v[94:97], v[142:145], v[208:211], v[94:97]
	v_mfma_f32_16x16x32_bf16 v[86:89], v[154:157], v[208:211], v[86:89]
	v_mfma_f32_16x16x32_bf16 v[78:81], v[142:145], v[230:233], v[78:81]
	v_mfma_f32_16x16x32_bf16 v[70:73], v[154:157], v[230:233], v[70:73]
	v_mfma_f32_16x16x32_bf16 v[126:129], v[150:153], v[182:185], v[126:129]
	v_mfma_f32_16x16x32_bf16 v[118:121], v[158:161], v[182:185], v[118:121]
	v_mfma_f32_16x16x32_bf16 v[110:113], v[150:153], v[190:193], v[110:113]
	v_mfma_f32_16x16x32_bf16 v[102:105], v[158:161], v[190:193], v[102:105]
	v_mfma_f32_16x16x32_bf16 v[94:97], v[150:153], v[226:229], v[94:97]
	v_mfma_f32_16x16x32_bf16 v[86:89], v[158:161], v[226:229], v[86:89]
	v_mfma_f32_16x16x32_bf16 v[78:81], v[150:153], v[234:237], v[78:81]
	v_mfma_f32_16x16x32_bf16 v[70:73], v[158:161], v[234:237], v[70:73]
	s_setprio 0
	s_setprio 1
	v_mfma_f32_16x16x32_bf16 v[130:133], v[162:165], v[178:181], v[130:133]
	v_mfma_f32_16x16x32_bf16 v[122:125], v[170:173], v[178:181], v[122:125]
	v_mfma_f32_16x16x32_bf16 v[114:117], v[162:165], v[186:189], v[114:117]
	v_mfma_f32_16x16x32_bf16 v[106:109], v[170:173], v[186:189], v[106:109]
	v_mfma_f32_16x16x32_bf16 v[98:101], v[162:165], v[208:211], v[98:101]
	v_mfma_f32_16x16x32_bf16 v[90:93], v[170:173], v[208:211], v[90:93]
	v_mfma_f32_16x16x32_bf16 v[82:85], v[162:165], v[230:233], v[82:85]
	v_mfma_f32_16x16x32_bf16 v[74:77], v[170:173], v[230:233], v[74:77]
	v_mfma_f32_16x16x32_bf16 v[130:133], v[166:169], v[182:185], v[130:133]
	v_mfma_f32_16x16x32_bf16 v[122:125], v[174:177], v[182:185], v[122:125]
	v_mfma_f32_16x16x32_bf16 v[114:117], v[166:169], v[190:193], v[114:117]
	v_mfma_f32_16x16x32_bf16 v[106:109], v[174:177], v[190:193], v[106:109]
	v_mfma_f32_16x16x32_bf16 v[98:101], v[166:169], v[226:229], v[98:101]
	v_mfma_f32_16x16x32_bf16 v[90:93], v[174:177], v[226:229], v[90:93]
	v_mfma_f32_16x16x32_bf16 v[82:85], v[166:169], v[234:237], v[82:85]
	v_mfma_f32_16x16x32_bf16 v[74:77], v[174:177], v[234:237], v[74:77]
	s_setprio 0
	s_barrier
; #define PG8_STAGE(bufoff, gbase, voff) do { _Pragma("unroll") for (int _i = 0; _i < 2; ++_i) \
;         __builtin_amdgcn_global_load_lds((const unsigned*)((const char*)(gbase) + (voff)[_i]), (PG8_LAS unsigned*)(lds + (bufoff) + ldsw + _i * 8192), 16, 0, 0); } while (0)
; #define PG8_LDA(dst, b, h) do { _Pragma("unroll") for (int m = 0; m < 4; ++m) _Pragma("unroll") for (int k = 0; k < 2; ++k) dst[m][k] = *(const PG8_LAS bf16x8*)(lds + PG8_SA(b, h) + aoff + m * 2048 + k * 1024); } while (0)
; #define PG8_MMA(ai, bj, At, Bt) do { __builtin_amdgcn_s_setprio(1); _Pragma("unroll") for (int m = 0; m < 4; ++m) _Pragma("unroll") for (int n = 0; n < 2; ++n) _Pragma("unroll") for (int k = 0; k < 2; ++k) \
;         acc[ai][bj][m][n] = __builtin_amdgcn_mfma_f32_16x16x32_bf16(Bt[n][k], At[m][k], acc[ai][bj][m][n], 0, 0, 0); __builtin_amdgcn_s_setprio(0); } while (0)
; #define PG8_WAIT_V(n) asm volatile("s_waitcnt vmcnt(" #n ")" ::: "memory")
; #define PG8_WAIT_L(n) asm volatile("s_waitcnt lgkmcnt(" #n ")" ::: "memory")
; #define PG8_BAR __builtin_amdgcn_s_barrier()
; #define PG8_SCHED __builtin_amdgcn_sched_barrier(0)
; template <class Epi, class Sched, bool ALIGN_EPI = false, bool SP2 = false>
; __device__ __forceinline__ void gemm_phase(PG8_LAS unsigned char* lds, const Gemm g, const Sched& S, const Epi& E, const int tid) {
;     ...
;         for (int t = 0; t < nt; t += 2) {
;             if constexpr (Epi::MIDK) { if (t == E.midk) E.mid(acc, cur, wr, fr); }
;             const bool last = (t == nt - 2);
;             const char* a1 = cA + (size_t)(t + 1) * kstep;
;             const char* a2 = last ? nA : cA + (size_t)(t + 2) * kstep; const char* b2 = last ? nB : cB + (size_t)(t + 2) * kstep;
;     ...
;             PG8_LDA(At, 1, 1); PG8_STAGE(PG8_SB(1, 0), b3, voffB); PG8_STAGE(PG8_SB(1, 1), b3 + hstep, voffB); PG8_STAGE(PG8_SA(1, 0), a3, voffA);
;             PG8_WAIT_V(8); PG8_WAIT_L(0); PG8_BAR; PG8_MMA(1, 0, At, B0); PG8_MMA(1, 1, At, B1); PG8_BAR; PG8_SCHED;
	s_add_i32 s46, s46, s19
	v_lshl_add_u64 v[194:195], v[194:195], 0, s[50:51]
	s_mov_b32 m0, s46
	ds_read_b128 v[178:181], v148 offset:49152
	ds_read_b128 v[182:185], v148 offset:50176
	ds_read_b128 v[186:189], v148 offset:51200
	ds_read_b128 v[190:193], v148 offset:52224
	ds_read_b128 v[208:211], v148 offset:53248
	ds_read_b128 v[226:229], v148 offset:54272
	ds_read_b128 v[230:233], v148 offset:55296
	ds_read_b128 v[234:237], v148 offset:56320
	global_load_lds_dwordx4 v[194:195], off
	s_add_i32 m0, s46, 0x2000
	s_add_u32 s54, s84, 0x40080
	v_lshl_add_u64 v[194:195], v[238:239], 0, s[50:51]
	s_addc_u32 s55, s85, 0
	s_add_i32 s46, s75, s19
	global_load_lds_dwordx4 v[194:195], off
	v_lshl_add_u64 v[194:195], s[54:55], 0, v[0:1]
	s_mov_b32 m0, s46
	s_nop 0
	global_load_lds_dwordx4 v[194:195], off
	v_lshl_add_u64 v[194:195], s[54:55], 0, v[2:3]
	s_add_i32 m0, s46, 0x2000
	s_nop 0
	global_load_lds_dwordx4 v[194:195], off
	v_lshl_add_u64 v[194:195], v[240:241], 0, s[50:51]
	s_mov_b32 m0, s28
	s_nop 0
	global_load_lds_dwordx4 v[194:195], off
	v_lshl_add_u64 v[194:195], v[242:243], 0, s[50:51]
	s_mov_b32 m0, s30
	s_nop 0
	global_load_lds_dwordx4 v[194:195], off
	s_waitcnt vmcnt(8)
	s_waitcnt lgkmcnt(0)
	s_barrier
	s_setprio 1
	s_waitcnt lgkmcnt(0)
	v_mfma_f32_16x16x32_bf16 v[62:65], v[142:145], v[178:181], v[62:65]
	v_mfma_f32_16x16x32_bf16 v[54:57], v[154:157], v[178:181], v[54:57]
	v_mfma_f32_16x16x32_bf16 v[46:49], v[142:145], v[186:189], v[46:49]
	v_mfma_f32_16x16x32_bf16 v[38:41], v[154:157], v[186:189], v[38:41]
	v_mfma_f32_16x16x32_bf16 v[30:33], v[142:145], v[208:211], v[30:33]
	v_mfma_f32_16x16x32_bf16 v[22:25], v[154:157], v[208:211], v[22:25]
	v_mfma_f32_16x16x32_bf16 v[14:17], v[142:145], v[230:233], v[14:17]
	v_mfma_f32_16x16x32_bf16 v[10:13], v[154:157], v[230:233], v[10:13]
	v_mfma_f32_16x16x32_bf16 v[62:65], v[150:153], v[182:185], v[62:65]
	v_mfma_f32_16x16x32_bf16 v[54:57], v[158:161], v[182:185], v[54:57]
	v_mfma_f32_16x16x32_bf16 v[46:49], v[150:153], v[190:193], v[46:49]
	v_mfma_f32_16x16x32_bf16 v[38:41], v[158:161], v[190:193], v[38:41]
	v_mfma_f32_16x16x32_bf16 v[30:33], v[150:153], v[226:229], v[30:33]
	v_mfma_f32_16x16x32_bf16 v[22:25], v[158:161], v[226:229], v[22:25]
	v_mfma_f32_16x16x32_bf16 v[14:17], v[150:153], v[234:237], v[14:17]
	v_mfma_f32_16x16x32_bf16 v[10:13], v[158:161], v[234:237], v[10:13]
	s_setprio 0
	s_setprio 1
	v_mfma_f32_16x16x32_bf16 v[66:69], v[162:165], v[178:181], v[66:69]
	v_mfma_f32_16x16x32_bf16 v[58:61], v[170:173], v[178:181], v[58:61]
	v_mfma_f32_16x16x32_bf16 v[50:53], v[162:165], v[186:189], v[50:53]
	v_mfma_f32_16x16x32_bf16 v[42:45], v[170:173], v[186:189], v[42:45]
	v_mfma_f32_16x16x32_bf16 v[34:37], v[162:165], v[208:211], v[34:37]
	v_mfma_f32_16x16x32_bf16 v[26:29], v[170:173], v[208:211], v[26:29]
	v_mfma_f32_16x16x32_bf16 v[18:21], v[162:165], v[230:233], v[18:21]
	v_mfma_f32_16x16x32_bf16 v[6:9], v[170:173], v[230:233], v[6:9]
	v_mfma_f32_16x16x32_bf16 v[66:69], v[166:169], v[182:185], v[66:69]
	v_mfma_f32_16x16x32_bf16 v[58:61], v[174:177], v[182:185], v[58:61]
	v_mfma_f32_16x16x32_bf16 v[50:53], v[166:169], v[190:193], v[50:53]
	v_mfma_f32_16x16x32_bf16 v[42:45], v[174:177], v[190:193], v[42:45]
	v_mfma_f32_16x16x32_bf16 v[34:37], v[166:169], v[226:229], v[34:37]
	v_mfma_f32_16x16x32_bf16 v[26:29], v[174:177], v[226:229], v[26:29]
	v_mfma_f32_16x16x32_bf16 v[18:21], v[166:169], v[234:237], v[18:21]
	v_mfma_f32_16x16x32_bf16 v[6:9], v[174:177], v[234:237], v[6:9]
	s_setprio 0
	s_barrier
	s_add_i32 s43, s43, 2
	s_add_u32 s40, s40, 0x100
	s_addc_u32 s42, s42, 0
	s_add_u32 s82, s82, 0x100
	s_addc_u32 s83, s83, 0
	s_cmp_gt_u32 s43, 13

; #define PG8_STAGE(bufoff, gbase, voff) do { _Pragma("unroll") for (int _i = 0; _i < 2; ++_i) \
;         __builtin_amdgcn_global_load_lds((const unsigned*)((const char*)(gbase) + (voff)[_i]), (PG8_LAS unsigned*)(lds + (bufoff) + ldsw + _i * 8192), 16, 0, 0); } while (0)
; #define PG8_LDA(dst, b, h) do { _Pragma("unroll") for (int m = 0; m < 4; ++m) _Pragma("unroll") for (int k = 0; k < 2; ++k) dst[m][k] = *(const PG8_LAS bf16x8*)(lds + PG8_SA(b, h) + aoff + m * 2048 + k * 1024); } while (0)
; #define PG8_LDB(dst, b, h) do { _Pragma("unroll") for (int n = 0; n < 2; ++n) _Pragma("unroll") for (int k = 0; k < 2; ++k) dst[n][k] = *(const PG8_LAS bf16x8*)(lds + PG8_SB(b, h) + boff + n * 2048 + k * 1024); } while (0)
; #define PG8_WAIT_V(n) asm volatile("s_waitcnt vmcnt(" #n ")" ::: "memory")
; #define PG8_WAIT_L(n) asm volatile("s_waitcnt lgkmcnt(" #n ")" ::: "memory")
; #define PG8_BAR __builtin_amdgcn_s_barrier()
; template <class Epi, class Sched, bool ALIGN_EPI = false, bool SP2 = false>
; __device__ __forceinline__ void gemm_phase(PG8_LAS unsigned char* lds, const Gemm g, const Sched& S, const Epi& E, const int tid) {
;     ...
;         const bool has_next = S.next(ui + 1, nxt);
;         const char* nA = has_next ? (const char*)g.A + (size_t)nxt.pm * tstep : cA; const char* nB = has_next ? (const char*)g.Bt + (size_t)nxt.pn * tstep : cB;
;         for (int t = 0; t < nt; t += 2) {
;             if constexpr (Epi::MIDK) { if (t == E.midk) E.mid(acc, cur, wr, fr); }
;             const bool last = (t == nt - 2);
;             const char* a1 = cA + (size_t)(t + 1) * kstep;
;             const char* a2 = last ? nA : cA + (size_t)(t + 2) * kstep; const char* b2 = last ? nB : cB + (size_t)(t + 2) * kstep;
;             const char* a3 = a2 + kstep; const char* b3 = b2 + kstep;
;             if (last && has_next) S.a_ready(nxt);
;             if constexpr (SP2) {
;             PG8_LDB(B0, 0, 0); PG8_LDB(B1, 0, 1); PG8_SCHED; PG8_LDA(At, 0, 0); PG8_STAGE(PG8_SA(1, 1), a1 + hstep, voffA);
;             PG8_WAIT_V(8); PG8_WAIT_L(0); PG8_BAR; PG8_MMA(0, 0, At, B0); PG8_MMA(0, 1, At, B1); PG8_BAR; PG8_SCHED;
;             PG8_LDA(At, 0, 1); PG8_STAGE(PG8_SB(0, 0), b2, voffB); PG8_STAGE(PG8_SB(0, 1), b2 + hstep, voffB); PG8_STAGE(PG8_SA(0, 0), a2, voffA);
;             PG8_WAIT_V(8); PG8_WAIT_L(0); PG8_BAR; PG8_MMA(1, 0, At, B0); PG8_MMA(1, 1, At, B1); PG8_BAR; PG8_SCHED;
.LBB0_253:
	s_ashr_i32 s81, s80, 31
	s_lshl_b64 s[24:25], s[80:81], 19
	s_add_u32 s84, s13, s24
	s_addc_u32 s85, s18, s25
	s_and_b64 s[24:25], s[4:5], exec
	s_cselect_b32 s17, s85, s7
	s_cselect_b32 s24, s84, s6
	s_ashr_i32 s83, s82, 31
	s_lshl_b64 s[42:43], s[82:83], 19
	s_add_u32 s86, s19, s42
	s_addc_u32 s87, s20, s43
	s_and_b64 s[42:43], s[4:5], exec
	s_cselect_b32 s25, s87, s89
	s_cselect_b32 s33, s86, s88
	s_add_u32 s40, s88, 0x100
	s_addc_u32 s42, s89, 0
	s_add_u32 s6, s6, 0x40080
	s_addc_u32 s7, s7, 0
	s_mov_b32 s43, -2
	s_waitcnt vmcnt(0)
	s_add_u32 s46, s6, 0xfffc0080
	s_addc_u32 s54, s7, -1
	s_add_i32 s55, 0, 0x10000
	s_cmp_eq_u32 s43, 12
	s_cselect_b32 s91, s17, s54
	s_cselect_b32 s90, s24, s46
	v_add_u32_e32 v0, s55, v164
	s_cselect_b32 s89, s25, s42
	s_cselect_b32 s88, s33, s40
	s_add_i32 s46, 0, 0x14000
	ds_read_b128 v[144:147], v0
	ds_read_b128 v[148:151], v0 offset:1024
	ds_read_b128 v[152:155], v0 offset:2048
	ds_read_b128 v[156:159], v0 offset:3072
	v_add_u32_e32 v0, s46, v164
	ds_read_b128 v[160:163], v0
	ds_read_b128 v[168:171], v0 offset:1024
	ds_read_b128 v[172:175], v0 offset:2048
	ds_read_b128 v[176:179], v0 offset:3072
	v_lshl_add_u64 v[238:239], s[6:7], 0, v[142:143]
	s_add_i32 m0, s30, 0xc000
	ds_read_b128 v[180:183], v166
	ds_read_b128 v[184:187], v166 offset:1024
	ds_read_b128 v[188:191], v166 offset:2048
	ds_read_b128 v[192:195], v166 offset:3072
	ds_read_b128 v[208:211], v166 offset:4096
	ds_read_b128 v[226:229], v166 offset:5120
	ds_read_b128 v[230:233], v166 offset:6144
	ds_read_b128 v[234:237], v166 offset:7168
	global_load_lds_dwordx4 v[238:239], off
	v_lshl_add_u64 v[238:239], s[6:7], 0, v[140:141]
	s_add_i32 m0, s30, 0xe000
	s_nop 0
	global_load_lds_dwordx4 v[238:239], off
	s_waitcnt vmcnt(8)
	s_waitcnt lgkmcnt(0)
	s_barrier
	s_setprio 1
	s_waitcnt lgkmcnt(0)
	v_mfma_f32_16x16x32_bf16 v[130:133], v[144:147], v[180:183], 0
	v_mfma_f32_16x16x32_bf16 v[126:129], v[152:155], v[180:183], 0
	v_mfma_f32_16x16x32_bf16 v[114:117], v[144:147], v[188:191], 0
	v_mfma_f32_16x16x32_bf16 v[110:113], v[152:155], v[188:191], 0
	v_mfma_f32_16x16x32_bf16 v[98:101], v[144:147], v[208:211], 0
	v_mfma_f32_16x16x32_bf16 v[94:97], v[152:155], v[208:211], 0
	v_mfma_f32_16x16x32_bf16 v[82:85], v[144:147], v[230:233], 0
	v_mfma_f32_16x16x32_bf16 v[78:81], v[152:155], v[230:233], 0
	v_mfma_f32_16x16x32_bf16 v[130:133], v[148:151], v[184:187], v[130:133]
	v_mfma_f32_16x16x32_bf16 v[126:129], v[156:159], v[184:187], v[126:129]
	v_mfma_f32_16x16x32_bf16 v[114:117], v[148:151], v[192:195], v[114:117]
	v_mfma_f32_16x16x32_bf16 v[110:113], v[156:159], v[192:195], v[110:113]
	v_mfma_f32_16x16x32_bf16 v[98:101], v[148:151], v[226:229], v[98:101]
	v_mfma_f32_16x16x32_bf16 v[94:97], v[156:159], v[226:229], v[94:97]
	v_mfma_f32_16x16x32_bf16 v[82:85], v[148:151], v[234:237], v[82:85]
	v_mfma_f32_16x16x32_bf16 v[78:81], v[156:159], v[234:237], v[78:81]
	s_setprio 0
	s_setprio 1
	v_mfma_f32_16x16x32_bf16 v[122:125], v[160:163], v[180:183], 0
	v_mfma_f32_16x16x32_bf16 v[118:121], v[172:175], v[180:183], 0
	v_mfma_f32_16x16x32_bf16 v[106:109], v[160:163], v[188:191], 0
	v_mfma_f32_16x16x32_bf16 v[102:105], v[172:175], v[188:191], 0
	v_mfma_f32_16x16x32_bf16 v[90:93], v[160:163], v[208:211], 0
	v_mfma_f32_16x16x32_bf16 v[86:89], v[172:175], v[208:211], 0
	v_mfma_f32_16x16x32_bf16 v[74:77], v[160:163], v[230:233], 0
	v_mfma_f32_16x16x32_bf16 v[70:73], v[172:175], v[230:233], 0
	v_mfma_f32_16x16x32_bf16 v[122:125], v[168:171], v[184:187], v[122:125]
	v_mfma_f32_16x16x32_bf16 v[118:121], v[176:179], v[184:187], v[118:121]
	v_mfma_f32_16x16x32_bf16 v[106:109], v[168:171], v[192:195], v[106:109]
	v_mfma_f32_16x16x32_bf16 v[102:105], v[176:179], v[192:195], v[102:105]
	v_mfma_f32_16x16x32_bf16 v[90:93], v[168:171], v[226:229], v[90:93]
	v_mfma_f32_16x16x32_bf16 v[86:89], v[176:179], v[226:229], v[86:89]
	v_mfma_f32_16x16x32_bf16 v[74:77], v[168:171], v[234:237], v[74:77]
	v_mfma_f32_16x16x32_bf16 v[70:73], v[176:179], v[234:237], v[70:73]
	s_setprio 0
	s_barrier
	s_add_i32 s54, s55, s28
	v_lshl_add_u64 v[238:239], s[88:89], 0, v[136:137]
	s_mov_b32 m0, s54
	ds_read_b128 v[180:183], v166 offset:16384
	ds_read_b128 v[184:187], v166 offset:17408
	ds_read_b128 v[188:191], v166 offset:18432
	ds_read_b128 v[192:195], v166 offset:19456
	ds_read_b128 v[208:211], v166 offset:20480
	ds_read_b128 v[226:229], v166 offset:21504
	ds_read_b128 v[230:233], v166 offset:22528
	ds_read_b128 v[234:237], v166 offset:23552
	global_load_lds_dwordx4 v[238:239], off
	s_add_i32 m0, s54, 0x2000
	s_add_u32 s54, s88, 0x40000
	v_lshl_add_u64 v[240:241], s[88:89], 0, v[2:3]
	s_addc_u32 s55, s89, 0
	s_add_i32 s46, s46, s28
	global_load_lds_dwordx4 v[240:241], off
	v_lshl_add_u64 v[242:243], s[54:55], 0, v[136:137]
	s_mov_b32 m0, s46
	v_lshl_add_u64 v[244:245], s[90:91], 0, v[134:135]
	global_load_lds_dwordx4 v[242:243], off
	v_lshl_add_u64 v[242:243], s[54:55], 0, v[2:3]
	s_add_i32 m0, s46, 0x2000
	s_nop 0
	global_load_lds_dwordx4 v[242:243], off
	v_lshl_add_u64 v[242:243], s[90:91], 0, v[138:139]
	s_mov_b32 m0, s30
	s_nop 0
	global_load_lds_dwordx4 v[242:243], off
	s_mov_b32 m0, s31
	s_nop 0
	global_load_lds_dwordx4 v[244:245], off
	s_waitcnt vmcnt(8)
	s_waitcnt lgkmcnt(0)
	s_barrier
; #define PG8_STAGE(bufoff, gbase, voff) do { _Pragma("unroll") for (int _i = 0; _i < 2; ++_i) \
;         __builtin_amdgcn_global_load_lds((const unsigned*)((const char*)(gbase) + (voff)[_i]), (PG8_LAS unsigned*)(lds + (bufoff) + ldsw + _i * 8192), 16, 0, 0); } while (0)
; #define PG8_LDA(dst, b, h) do { _Pragma("unroll") for (int m = 0; m < 4; ++m) _Pragma("unroll") for (int k = 0; k < 2; ++k) dst[m][k] = *(const PG8_LAS bf16x8*)(lds + PG8_SA(b, h) + aoff + m * 2048 + k * 1024); } while (0)
; #define PG8_LDB(dst, b, h) do { _Pragma("unroll") for (int n = 0; n < 2; ++n) _Pragma("unroll") for (int k = 0; k < 2; ++k) dst[n][k] = *(const PG8_LAS bf16x8*)(lds + PG8_SB(b, h) + boff + n * 2048 + k * 1024); } while (0)
; #define PG8_MMA(ai, bj, At, Bt) do { __builtin_amdgcn_s_setprio(1); _Pragma("unroll") for (int m = 0; m < 4; ++m) _Pragma("unroll") for (int n = 0; n < 2; ++n) _Pragma("unroll") for (int k = 0; k < 2; ++k) \
;         acc[ai][bj][m][n] = __builtin_amdgcn_mfma_f32_16x16x32_bf16(Bt[n][k], At[m][k], acc[ai][bj][m][n], 0, 0, 0); __builtin_amdgcn_s_setprio(0); } while (0)
; #define PG8_WAIT_V(n) asm volatile("s_waitcnt vmcnt(" #n ")" ::: "memory")
; #define PG8_WAIT_L(n) asm volatile("s_waitcnt lgkmcnt(" #n ")" ::: "memory")
; #define PG8_BAR __builtin_amdgcn_s_barrier()
; #define PG8_SCHED __builtin_amdgcn_sched_barrier(0)
; template <class Epi, class Sched, bool ALIGN_EPI = false, bool SP2 = false>
; __device__ __forceinline__ void gemm_phase(PG8_LAS unsigned char* lds, const Gemm g, const Sched& S, const Epi& E, const int tid) {
;     ...
;             PG8_WAIT_V(8); PG8_WAIT_L(0); PG8_BAR; PG8_MMA(1, 0, At, B0); PG8_MMA(1, 1, At, B1); PG8_BAR; PG8_SCHED;
;             PG8_LDB(B0, 1, 0); PG8_LDB(B1, 1, 1); PG8_SCHED; PG8_LDA(At, 1, 0); PG8_STAGE(PG8_SA(0, 1), a2 + hstep, voffA);
;             PG8_WAIT_V(8); PG8_WAIT_L(0); PG8_BAR; PG8_MMA(0, 0, At, B0); PG8_MMA(0, 1, At, B1); PG8_BAR; PG8_SCHED;
	s_setprio 1
	s_waitcnt lgkmcnt(0)
	v_mfma_f32_16x16x32_bf16 v[66:69], v[144:147], v[180:183], 0
	v_mfma_f32_16x16x32_bf16 v[62:65], v[152:155], v[180:183], 0
	v_mfma_f32_16x16x32_bf16 v[50:53], v[144:147], v[188:191], 0
	v_mfma_f32_16x16x32_bf16 v[46:49], v[152:155], v[188:191], 0
	v_mfma_f32_16x16x32_bf16 v[34:37], v[144:147], v[208:211], 0
	v_mfma_f32_16x16x32_bf16 v[30:33], v[152:155], v[208:211], 0
	v_mfma_f32_16x16x32_bf16 v[18:21], v[144:147], v[230:233], 0
	v_mfma_f32_16x16x32_bf16 v[14:17], v[152:155], v[230:233], 0
	v_mfma_f32_16x16x32_bf16 v[66:69], v[148:151], v[184:187], v[66:69]
	v_mfma_f32_16x16x32_bf16 v[62:65], v[156:159], v[184:187], v[62:65]
	v_mfma_f32_16x16x32_bf16 v[50:53], v[148:151], v[192:195], v[50:53]
	v_mfma_f32_16x16x32_bf16 v[46:49], v[156:159], v[192:195], v[46:49]
	v_mfma_f32_16x16x32_bf16 v[34:37], v[148:151], v[226:229], v[34:37]
	v_mfma_f32_16x16x32_bf16 v[30:33], v[156:159], v[226:229], v[30:33]
	v_mfma_f32_16x16x32_bf16 v[18:21], v[148:151], v[234:237], v[18:21]
	v_mfma_f32_16x16x32_bf16 v[14:17], v[156:159], v[234:237], v[14:17]
	s_setprio 0
	s_setprio 1
	v_mfma_f32_16x16x32_bf16 v[58:61], v[160:163], v[180:183], 0
	v_mfma_f32_16x16x32_bf16 v[54:57], v[172:175], v[180:183], 0
	v_mfma_f32_16x16x32_bf16 v[42:45], v[160:163], v[188:191], 0
	v_mfma_f32_16x16x32_bf16 v[38:41], v[172:175], v[188:191], 0
	v_mfma_f32_16x16x32_bf16 v[26:29], v[160:163], v[208:211], 0
	v_mfma_f32_16x16x32_bf16 v[22:25], v[172:175], v[208:211], 0
	v_mfma_f32_16x16x32_bf16 v[10:13], v[160:163], v[230:233], 0
	v_mfma_f32_16x16x32_bf16 v[6:9], v[172:175], v[230:233], 0
	v_mfma_f32_16x16x32_bf16 v[58:61], v[168:171], v[184:187], v[58:61]
	v_mfma_f32_16x16x32_bf16 v[54:57], v[176:179], v[184:187], v[54:57]
	v_mfma_f32_16x16x32_bf16 v[42:45], v[168:171], v[192:195], v[42:45]
	v_mfma_f32_16x16x32_bf16 v[38:41], v[176:179], v[192:195], v[38:41]
	v_mfma_f32_16x16x32_bf16 v[26:29], v[168:171], v[226:229], v[26:29]
	v_mfma_f32_16x16x32_bf16 v[22:25], v[176:179], v[226:229], v[22:25]
	v_mfma_f32_16x16x32_bf16 v[10:13], v[168:171], v[234:237], v[10:13]
	v_mfma_f32_16x16x32_bf16 v[6:9], v[176:179], v[234:237], v[6:9]
	s_setprio 0
	s_barrier
	s_add_i32 s46, 0, 0x18000
	v_add_u32_e32 v0, s46, v164
	s_add_i32 s81, 0, 0x1c000
	ds_read_b128 v[144:147], v0
	ds_read_b128 v[148:151], v0 offset:1024
	ds_read_b128 v[152:155], v0 offset:2048
	ds_read_b128 v[156:159], v0 offset:3072
	v_add_u32_e32 v0, s81, v164
	ds_read_b128 v[160:163], v0
	ds_read_b128 v[168:171], v0 offset:1024
	ds_read_b128 v[172:175], v0 offset:2048
	ds_read_b128 v[176:179], v0 offset:3072
	s_add_u32 s54, s90, 0x40000
	s_addc_u32 s55, s91, 0
	s_mov_b32 m0, s34
	v_lshl_add_u64 v[246:247], s[54:55], 0, v[138:139]
	ds_read_b128 v[180:183], v166 offset:32768
	ds_read_b128 v[184:187], v166 offset:33792
	ds_read_b128 v[188:191], v166 offset:34816
	ds_read_b128 v[192:195], v166 offset:35840
	ds_read_b128 v[208:211], v166 offset:36864
	ds_read_b128 v[226:229], v166 offset:37888
	ds_read_b128 v[230:233], v166 offset:38912
	ds_read_b128 v[234:237], v166 offset:39936
	global_load_lds_dwordx4 v[246:247], off
	v_lshl_add_u64 v[246:247], s[54:55], 0, v[134:135]
	s_mov_b32 m0, s36
	s_nop 0
	global_load_lds_dwordx4 v[246:247], off
	s_waitcnt vmcnt(8)
	s_waitcnt lgkmcnt(0)
	s_barrier
	s_setprio 1
	s_waitcnt lgkmcnt(0)
	v_mfma_f32_16x16x32_bf16 v[130:133], v[144:147], v[180:183], v[130:133]
	v_mfma_f32_16x16x32_bf16 v[126:129], v[152:155], v[180:183], v[126:129]
	v_mfma_f32_16x16x32_bf16 v[114:117], v[144:147], v[188:191], v[114:117]
	v_mfma_f32_16x16x32_bf16 v[110:113], v[152:155], v[188:191], v[110:113]
	v_mfma_f32_16x16x32_bf16 v[98:101], v[144:147], v[208:211], v[98:101]
	v_mfma_f32_16x16x32_bf16 v[94:97], v[152:155], v[208:211], v[94:97]
	v_mfma_f32_16x16x32_bf16 v[82:85], v[144:147], v[230:233], v[82:85]
	v_mfma_f32_16x16x32_bf16 v[78:81], v[152:155], v[230:233], v[78:81]
	v_mfma_f32_16x16x32_bf16 v[130:133], v[148:151], v[184:187], v[130:133]
	v_mfma_f32_16x16x32_bf16 v[126:129], v[156:159], v[184:187], v[126:129]
	v_mfma_f32_16x16x32_bf16 v[114:117], v[148:151], v[192:195], v[114:117]
	v_mfma_f32_16x16x32_bf16 v[110:113], v[156:159], v[192:195], v[110:113]
	v_mfma_f32_16x16x32_bf16 v[98:101], v[148:151], v[226:229], v[98:101]
	v_mfma_f32_16x16x32_bf16 v[94:97], v[156:159], v[226:229], v[94:97]
	v_mfma_f32_16x16x32_bf16 v[82:85], v[148:151], v[234:237], v[82:85]
	v_mfma_f32_16x16x32_bf16 v[78:81], v[156:159], v[234:237], v[78:81]
	s_setprio 0
	s_setprio 1
	v_mfma_f32_16x16x32_bf16 v[122:125], v[160:163], v[180:183], v[122:125]
	v_mfma_f32_16x16x32_bf16 v[118:121], v[172:175], v[180:183], v[118:121]
	v_mfma_f32_16x16x32_bf16 v[106:109], v[160:163], v[188:191], v[106:109]
	v_mfma_f32_16x16x32_bf16 v[102:105], v[172:175], v[188:191], v[102:105]
	v_mfma_f32_16x16x32_bf16 v[90:93], v[160:163], v[208:211], v[90:93]
	v_mfma_f32_16x16x32_bf16 v[86:89], v[172:175], v[208:211], v[86:89]
	v_mfma_f32_16x16x32_bf16 v[74:77], v[160:163], v[230:233], v[74:77]
	v_mfma_f32_16x16x32_bf16 v[70:73], v[172:175], v[230:233], v[70:73]
	v_mfma_f32_16x16x32_bf16 v[122:125], v[168:171], v[184:187], v[122:125]
	v_mfma_f32_16x16x32_bf16 v[118:121], v[176:179], v[184:187], v[118:121]
	v_mfma_f32_16x16x32_bf16 v[106:109], v[168:171], v[192:195], v[106:109]
	v_mfma_f32_16x16x32_bf16 v[102:105], v[176:179], v[192:195], v[102:105]
	v_mfma_f32_16x16x32_bf16 v[90:93], v[168:171], v[226:229], v[90:93]
	v_mfma_f32_16x16x32_bf16 v[86:89], v[176:179], v[226:229], v[86:89]
	v_mfma_f32_16x16x32_bf16 v[74:77], v[168:171], v[234:237], v[74:77]
	v_mfma_f32_16x16x32_bf16 v[70:73], v[176:179], v[234:237], v[70:73]
	s_setprio 0
	s_barrier
; #define PG8_STAGE(bufoff, gbase, voff) do { _Pragma("unroll") for (int _i = 0; _i < 2; ++_i) \
;         __builtin_amdgcn_global_load_lds((const unsigned*)((const char*)(gbase) + (voff)[_i]), (PG8_LAS unsigned*)(lds + (bufoff) + ldsw + _i * 8192), 16, 0, 0); } while (0)
; #define PG8_LDA(dst, b, h) do { _Pragma("unroll") for (int m = 0; m < 4; ++m) _Pragma("unroll") for (int k = 0; k < 2; ++k) dst[m][k] = *(const PG8_LAS bf16x8*)(lds + PG8_SA(b, h) + aoff + m * 2048 + k * 1024); } while (0)
; #define PG8_MMA(ai, bj, At, Bt) do { __builtin_amdgcn_s_setprio(1); _Pragma("unroll") for (int m = 0; m < 4; ++m) _Pragma("unroll") for (int n = 0; n < 2; ++n) _Pragma("unroll") for (int k = 0; k < 2; ++k) \
;         acc[ai][bj][m][n] = __builtin_amdgcn_mfma_f32_16x16x32_bf16(Bt[n][k], At[m][k], acc[ai][bj][m][n], 0, 0, 0); __builtin_amdgcn_s_setprio(0); } while (0)
; #define PG8_WAIT_V(n) asm volatile("s_waitcnt vmcnt(" #n ")" ::: "memory")
; #define PG8_WAIT_L(n) asm volatile("s_waitcnt lgkmcnt(" #n ")" ::: "memory")
; #define PG8_BAR __builtin_amdgcn_s_barrier()
; #define PG8_SCHED __builtin_amdgcn_sched_barrier(0)
; template <class Epi, class Sched, bool ALIGN_EPI = false, bool SP2 = false>
; __device__ __forceinline__ void gemm_phase(PG8_LAS unsigned char* lds, const Gemm g, const Sched& S, const Epi& E, const int tid) {
;     ...
;         for (int t = 0; t < nt; t += 2) {
;             if constexpr (Epi::MIDK) { if (t == E.midk) E.mid(acc, cur, wr, fr); }
;             const bool last = (t == nt - 2);
;             const char* a1 = cA + (size_t)(t + 1) * kstep;
;             const char* a2 = last ? nA : cA + (size_t)(t + 2) * kstep; const char* b2 = last ? nB : cB + (size_t)(t + 2) * kstep;
;     ...
;             PG8_LDA(At, 1, 1); PG8_STAGE(PG8_SB(1, 0), b3, voffB); PG8_STAGE(PG8_SB(1, 1), b3 + hstep, voffB); PG8_STAGE(PG8_SA(1, 0), a3, voffA);
;             PG8_WAIT_V(8); PG8_WAIT_L(0); PG8_BAR; PG8_MMA(1, 0, At, B0); PG8_MMA(1, 1, At, B1); PG8_BAR; PG8_SCHED;
	s_add_i32 s46, s46, s28
	v_lshl_add_u64 v[238:239], v[238:239], 0, s[50:51]
	s_mov_b32 m0, s46
	ds_read_b128 v[180:183], v166 offset:49152
	ds_read_b128 v[184:187], v166 offset:50176
	ds_read_b128 v[188:191], v166 offset:51200
	ds_read_b128 v[192:195], v166 offset:52224
	ds_read_b128 v[208:211], v166 offset:53248
	ds_read_b128 v[226:229], v166 offset:54272
	ds_read_b128 v[230:233], v166 offset:55296
	ds_read_b128 v[234:237], v166 offset:56320
	global_load_lds_dwordx4 v[238:239], off
	s_add_i32 m0, s46, 0x2000
	s_add_u32 s54, s88, 0x40080
	v_lshl_add_u64 v[238:239], v[240:241], 0, s[50:51]
	s_addc_u32 s55, s89, 0
	s_add_i32 s46, s81, s28
	global_load_lds_dwordx4 v[238:239], off
	v_lshl_add_u64 v[238:239], s[54:55], 0, v[136:137]
	s_mov_b32 m0, s46
	s_nop 0
	global_load_lds_dwordx4 v[238:239], off
	v_lshl_add_u64 v[238:239], s[54:55], 0, v[2:3]
	s_add_i32 m0, s46, 0x2000
	s_nop 0
	global_load_lds_dwordx4 v[238:239], off
	v_lshl_add_u64 v[238:239], v[242:243], 0, s[50:51]
	s_mov_b32 m0, s37
	s_nop 0
	global_load_lds_dwordx4 v[238:239], off
	v_lshl_add_u64 v[238:239], v[244:245], 0, s[50:51]
	s_mov_b32 m0, s38
	s_nop 0
	global_load_lds_dwordx4 v[238:239], off
	s_waitcnt vmcnt(8)
	s_waitcnt lgkmcnt(0)
	s_barrier
	s_setprio 1
	s_waitcnt lgkmcnt(0)
	v_mfma_f32_16x16x32_bf16 v[66:69], v[144:147], v[180:183], v[66:69]
	v_mfma_f32_16x16x32_bf16 v[62:65], v[152:155], v[180:183], v[62:65]
	v_mfma_f32_16x16x32_bf16 v[50:53], v[144:147], v[188:191], v[50:53]
	v_mfma_f32_16x16x32_bf16 v[46:49], v[152:155], v[188:191], v[46:49]
	v_mfma_f32_16x16x32_bf16 v[34:37], v[144:147], v[208:211], v[34:37]
	v_mfma_f32_16x16x32_bf16 v[30:33], v[152:155], v[208:211], v[30:33]
	v_mfma_f32_16x16x32_bf16 v[18:21], v[144:147], v[230:233], v[18:21]
	v_mfma_f32_16x16x32_bf16 v[14:17], v[152:155], v[230:233], v[14:17]
	v_mfma_f32_16x16x32_bf16 v[66:69], v[148:151], v[184:187], v[66:69]
	v_mfma_f32_16x16x32_bf16 v[62:65], v[156:159], v[184:187], v[62:65]
	v_mfma_f32_16x16x32_bf16 v[50:53], v[148:151], v[192:195], v[50:53]
	v_mfma_f32_16x16x32_bf16 v[46:49], v[156:159], v[192:195], v[46:49]
	v_mfma_f32_16x16x32_bf16 v[34:37], v[148:151], v[226:229], v[34:37]
	v_mfma_f32_16x16x32_bf16 v[30:33], v[156:159], v[226:229], v[30:33]
	v_mfma_f32_16x16x32_bf16 v[18:21], v[148:151], v[234:237], v[18:21]
	v_mfma_f32_16x16x32_bf16 v[14:17], v[156:159], v[234:237], v[14:17]
	s_setprio 0
	s_setprio 1
	v_mfma_f32_16x16x32_bf16 v[58:61], v[160:163], v[180:183], v[58:61]
	v_mfma_f32_16x16x32_bf16 v[54:57], v[172:175], v[180:183], v[54:57]
	v_mfma_f32_16x16x32_bf16 v[42:45], v[160:163], v[188:191], v[42:45]
	v_mfma_f32_16x16x32_bf16 v[38:41], v[172:175], v[188:191], v[38:41]
	v_mfma_f32_16x16x32_bf16 v[26:29], v[160:163], v[208:211], v[26:29]
	v_mfma_f32_16x16x32_bf16 v[22:25], v[172:175], v[208:211], v[22:25]
	v_mfma_f32_16x16x32_bf16 v[10:13], v[160:163], v[230:233], v[10:13]
	v_mfma_f32_16x16x32_bf16 v[6:9], v[172:175], v[230:233], v[6:9]
	v_mfma_f32_16x16x32_bf16 v[58:61], v[168:171], v[184:187], v[58:61]
	v_mfma_f32_16x16x32_bf16 v[54:57], v[176:179], v[184:187], v[54:57]
	v_mfma_f32_16x16x32_bf16 v[42:45], v[168:171], v[192:195], v[42:45]
	v_mfma_f32_16x16x32_bf16 v[38:41], v[176:179], v[192:195], v[38:41]
	v_mfma_f32_16x16x32_bf16 v[26:29], v[168:171], v[226:229], v[26:29]
	v_mfma_f32_16x16x32_bf16 v[22:25], v[176:179], v[226:229], v[22:25]
	v_mfma_f32_16x16x32_bf16 v[10:13], v[168:171], v[234:237], v[10:13]
	v_mfma_f32_16x16x32_bf16 v[6:9], v[176:179], v[234:237], v[6:9]
	s_setprio 0
	s_barrier
	s_add_i32 s43, s43, 2
	s_add_u32 s40, s40, 0x100
	s_addc_u32 s42, s42, 0
	s_add_u32 s6, s6, 0x100
	s_addc_u32 s7, s7, 0
	s_cmp_gt_u32 s43, 13
